# st5 sub-unit accumulator zeroing with v_mov_b64 (32 instead of 64 moves)
# speedup vs baseline: 1.0480x; 1.0043x over previous
.LBB0_118:
	v_mov_b32_e32 v0, 0
	s_mov_b64 s[24:25], 0
	s_mov_b64 s[12:13], -1
	s_mov_b64 s[22:23], 0
	v_mov_b32_e32 v1, v0
	v_mov_b64_e32 v[2:3], v[0:1]
	v_mov_b64_e32 v[4:5], v[0:1]
	v_mov_b64_e32 v[6:7], v[0:1]
	v_mov_b64_e32 v[8:9], v[0:1]
	v_mov_b64_e32 v[10:11], v[0:1]
	v_mov_b64_e32 v[12:13], v[0:1]
	v_mov_b64_e32 v[14:15], v[0:1]
	v_mov_b64_e32 v[16:17], v[0:1]
	v_mov_b64_e32 v[18:19], v[0:1]
	v_mov_b64_e32 v[20:21], v[0:1]
	v_mov_b64_e32 v[22:23], v[0:1]
	v_mov_b64_e32 v[24:25], v[0:1]
	v_mov_b64_e32 v[26:27], v[0:1]
	v_mov_b64_e32 v[28:29], v[0:1]
	v_mov_b64_e32 v[30:31], v[0:1]
	v_mov_b64_e32 v[32:33], v[0:1]
	v_mov_b64_e32 v[34:35], v[0:1]
	v_mov_b64_e32 v[36:37], v[0:1]
	v_mov_b64_e32 v[38:39], v[0:1]
	v_mov_b64_e32 v[40:41], v[0:1]
	v_mov_b64_e32 v[42:43], v[0:1]
	v_mov_b64_e32 v[44:45], v[0:1]
	v_mov_b64_e32 v[46:47], v[0:1]
	v_mov_b64_e32 v[48:49], v[0:1]
	v_mov_b64_e32 v[50:51], v[0:1]
	v_mov_b64_e32 v[52:53], v[0:1]
	v_mov_b64_e32 v[54:55], v[0:1]
	v_mov_b64_e32 v[56:57], v[0:1]
	v_mov_b64_e32 v[58:59], v[0:1]
	v_mov_b64_e32 v[60:61], v[0:1]
	v_mov_b64_e32 v[62:63], v[0:1]
